# merge-phase stagger of the second-half blocks lengthened (s_sleep 24 -> 100) on top of the DMA+priority GEMM mainloops
# speedup vs baseline: 1.0690x; 1.0010x over previous
.LBB0_846:
	s_or_b64 exec, exec, s[0:1]
	v_readlane_b32 s0, v249, 30
	v_readlane_b32 s1, v249, 31
	s_andn2_b64 vcc, exec, s[0:1]
	s_waitcnt lgkmcnt(0)
	s_barrier
	s_cbranch_vccnz .LBB0_848
	s_sleep 100
